# post_norm row loads software-pipelined (prefetch next iteration), census loads batched, tr_item gain loads batched
# speedup vs baseline: 1.0067x; 1.0053x over previous
; __device__ __forceinline__ unsigned xb_ld(unsigned* p)              { return __hip_atomic_load(p, __ATOMIC_RELAXED, __HIP_MEMORY_SCOPE_AGENT); }
; __device__ __forceinline__ void xcd_barrier_complete(unsigned* bar, unsigned x, unsigned& nloc, unsigned& nx) {
;     const unsigned G = gridDim.x * gridDim.y * gridDim.z;
;     unsigned sum, cnt, mine, sp = 0u;
;     for (;;) {
;         sum = 0u; cnt = 0u; mine = 0u;
; #pragma unroll
;         for (unsigned j = 0; j < 16; ++j) { const unsigned c = xb_ld(&bar[XB_XCNT(j)]); sum += c; cnt += (c > 0u) ? 1u : 0u; mine = (j == x) ? c : mine; }
;         if (sum == G) break;
;         __builtin_amdgcn_s_sleep(1);
;         if ((++sp & 255u) == 0u) { if (xb_ld(&bar[XB_TMO])) break; if (sp > XB_SPIN_CAP) { atomicAdd(&bar[XB_TMO], 1u); break; } }
;     }
;     nloc = mine > 0u ? mine : 1u; nx = cnt > 0u ? cnt : 1u;
.LBB0_195:
	s_waitcnt lgkmcnt(0)
	global_load_dword v4, v1, s[86:87] sc1
	global_load_dword v0, v1, s[86:87] offset:256 sc1
	global_load_dword v2, v1, s[86:87] offset:512 sc1
	global_load_dword v3, v1, s[86:87] offset:768 sc1
	global_load_dword v5, v1, s[86:87] offset:1024 sc1
	global_load_dword v6, v1, s[86:87] offset:1280 sc1
	global_load_dword v7, v1, s[86:87] offset:1536 sc1
	global_load_dword v8, v1, s[86:87] offset:1792 sc1
	global_load_dword v9, v1, s[86:87] offset:2048 sc1
	global_load_dword v10, v1, s[86:87] offset:2304 sc1
	global_load_dword v11, v1, s[86:87] offset:2560 sc1
	global_load_dword v12, v1, s[86:87] offset:2816 sc1
	global_load_dword v13, v1, s[86:87] offset:3072 sc1
	global_load_dword v14, v1, s[86:87] offset:3328 sc1
	global_load_dword v15, v1, s[86:87] offset:3584 sc1
	global_load_dword v16, v1, s[86:87] offset:3840 sc1
	s_mov_b64 s[6:7], -1
	s_mov_b64 s[4:5], -1
	s_waitcnt vmcnt(0)
	v_add_u32_e32 v17, v0, v4
	v_add3_u32 v17, v17, v2, v3
	v_add3_u32 v17, v17, v5, v6
	v_add3_u32 v17, v17, v7, v8
	v_add3_u32 v17, v17, v9, v10
	v_add3_u32 v17, v17, v11, v12
	v_add3_u32 v17, v17, v13, v14
	v_add3_u32 v17, v17, v15, v16
	v_cmp_eq_u32_e32 vcc, s82, v17
	s_cbranch_vccnz .LBB0_194
	s_and_b32 s4, s1, 0xff
	s_cmp_eq_u32 s4, 0
	s_mov_b64 s[4:5], -1
	s_mov_b64 s[10:11], -1
	s_sleep 1
	s_cbranch_scc0 .LBB0_199
	v_readlane_b32 s4, v252, 8
	v_readlane_b32 s5, v252, 9
	s_nop 4
	global_load_dword v17, v1, s[4:5] sc1
	s_waitcnt vmcnt(0)
	v_cmp_eq_u32_e32 vcc, 0, v17
	s_cbranch_vccnz .LBB0_201
	s_mov_b64 s[10:11], 0
	s_mov_b64 s[4:5], -1

; DI int tid_of(int wv) { int ln; asm volatile("v_mbcnt_lo_u32_b32 %0, -1, 0\n\tv_mbcnt_hi_u32_b32 %0, -1, %0" : "=v"(ln)); return wv * 64 + ln; }
; DI void post_norm(const P& p, int l, int nb, int bi, int wv) {
;     const int tid = tid_of(wv), lane = tid & 63, wave = tid >> 6, sub = lane & 15;
;     bf16* heads = (bf16*)(p.ws + WS_HEADS);
;     const int gw = bi * NWAVES + wave, NGW = nb * NWAVES;
;     constexpr int NIT = 12 * (M / 8);
;     for (int it = gw; it < NIT; it += NGW) {
;         const int si = it / (M / 8), r8 = it % (M / 8);
;         const int slot = si < 8 ? 8 + si : 20 + si;
;         const float* gp = (slot < 16 ? p.fkn : (slot < 30 ? p.skn : p.wkn)) + l * HD + sub * 8;
;         bf16* rowp0 = heads + ((size_t)slot * M + r8 * 8 + (lane >> 4)) * HD + sub * 8; bf16* rowp1 = rowp0 + 4 * HD;
;         const u32x4 raw0 = *(const u32x4*)rowp0, raw1 = *(const u32x4*)rowp1;
.LBB0_243:
	s_or_b64 exec, exec, s[2:3]
	s_cmp_lt_i32 s54, 16
	s_cselect_b64 s[2:3], -1, 0
	s_cmp_gt_i32 s54, 15
	s_cselect_b64 s[4:5], -1, 0
	s_sub_i32 s1, s54, 48
	s_cmp_gt_u32 s1, 0xffffffdf
	s_waitcnt lgkmcnt(0)
	s_barrier
	s_cbranch_scc1 .LBB0_248
	v_readlane_b32 s6, v252, 5
	v_mbcnt_lo_u32_b32 v0, -1, 0
	v_mbcnt_hi_u32_b32 v0, -1, v0
	s_nop 1
	v_add_u32_e32 v2, s6, v0
	s_lshl_b32 s6, s54, 3
	s_add_i32 s7, s6, 0xffffff00
	s_and_b64 s[2:3], s[2:3], exec
	v_ashrrev_i32_e32 v2, 6, v2
	s_cselect_b32 s2, s6, s7
	v_add_u32_e32 v3, s2, v2
	s_movk_i32 s2, 0x6000
	v_cmp_gt_i32_e32 vcc, s2, v3
	s_and_saveexec_b64 s[6:7], vcc
	v_readlane_b32 s14, v252, 3
	v_readlane_b32 s15, v252, 4
	s_cbranch_execz .LBB0_247
	v_readlane_b32 s2, v254, 51
	v_lshlrev_b32_e32 v2, 3, v0
	s_lshl_b32 s9, s2, 3
	v_and_b32_e32 v6, 0x78, v2
	v_readlane_b32 s2, v253, 10
	v_and_b32_e32 v7, 63, v0
	v_bfe_u32 v2, v0, 4, 2
	v_lshlrev_b32_e32 v0, 1, v6
	v_readlane_b32 s3, v253, 11
	s_addk_i32 s9, 0xff00
	s_lshl_b32 s16, s8, 7
	v_lshl_add_u64 v[4:5], s[2:3], 0, v[0:1]
	v_lshlrev_b32_e32 v0, 2, v7
	v_xor_b32_e32 v10, 4, v0
	v_xor_b32_e32 v11, 8, v0
	v_xor_b32_e32 v12, 16, v0
	v_xor_b32_e32 v13, 32, v0
	v_lshlrev_b32_e32 v14, 3, v3
	s_lshl_b32 s12, s9, 3
	s_mov_b64 s[10:11], 0
	v_lshlrev_b32_e32 v6, 2, v6
	v_ashrrev_i32_e32 v176, 31, v3
	v_lshrrev_b32_e32 v176, 21, v176
	v_cmp_gt_i32_e32 vcc, 0x4000, v3
	v_add_u32_e32 v176, v3, v176
	v_ashrrev_i32_e32 v176, 11, v176
	v_cndmask_b32_e64 v177, 20, 8, vcc
	v_add_u32_e32 v178, v177, v176
	v_mul_i32_i24_e32 v180, 0x800, v176
	v_lshlrev_b32_e32 v177, 3, v180
	v_ashrrev_i32_e32 v179, 31, v178
	v_sub_u32_e32 v182, v14, v177
	v_lshlrev_b64 v[178:179], 14, v[178:179]
	v_ashrrev_i32_e32 v183, 31, v182
	v_lshl_add_u64 v[178:179], v[178:179], 0, v[182:183]
	v_or_b32_e32 v178, v178, v2
	v_lshlrev_b64 v[178:179], 8, v[178:179]
	v_lshl_add_u64 v[178:179], v[4:5], 0, v[178:179]
	global_load_dwordx4 v[160:163], v[178:179], off
	global_load_dwordx4 v[164:167], v[178:179], off offset:1024
; DI float shx(float v, int m, int lane) { return __builtin_bit_cast(float, __builtin_amdgcn_ds_bpermute((lane ^ m) << 2, __builtin_bit_cast(int, v))); }
; DI unsigned pk2(float lo, float hi) { f32x2_t v = {lo, hi}; bf16x2_t b = __builtin_convertvector(v, bf16x2_t); return __builtin_bit_cast(unsigned, b); }
; DI void post_norm(const P& p, int l, int nb, int bi, int wv) {
;     ...
;     for (int it = gw; it < NIT; it += NGW) {
;         const int si = it / (M / 8), r8 = it % (M / 8);
;         const int slot = si < 8 ? 8 + si : 20 + si;
;         const float* gp = (slot < 16 ? p.fkn : (slot < 30 ? p.skn : p.wkn)) + l * HD + sub * 8;
;         bf16* rowp0 = heads + ((size_t)slot * M + r8 * 8 + (lane >> 4)) * HD + sub * 8; bf16* rowp1 = rowp0 + 4 * HD;
;         const u32x4 raw0 = *(const u32x4*)rowp0, raw1 = *(const u32x4*)rowp1;
;         const f32x4 g0 = *(const f32x4*)gp, g1 = *(const f32x4*)(gp + 4);
;         float v[8], u[8]; float s0 = 0.f, s1 = 0.f;
; #pragma unroll
;         for (int j = 0; j < 4; ++j) { v[2 * j] = __builtin_bit_cast(float, raw0[j] << 16); v[2 * j + 1] = __builtin_bit_cast(float, raw0[j] & 0xffff0000u);
;             u[2 * j] = __builtin_bit_cast(float, raw1[j] << 16); u[2 * j + 1] = __builtin_bit_cast(float, raw1[j] & 0xffff0000u); }
; #pragma unroll
;         for (int j = 0; j < 8; ++j) { s0 += v[j] * v[j]; s1 += u[j] * u[j]; }
;         s0 += shx(s0, 1, lane); s1 += shx(s1, 1, lane); s0 += shx(s0, 2, lane); s1 += shx(s1, 2, lane);
;         s0 += shx(s0, 4, lane); s1 += shx(s1, 4, lane); s0 += shx(s0, 8, lane); s1 += shx(s1, 8, lane);
;         const float r0 = rsqrtf(s0 * (1.0f / HD) + EPS), r1 = rsqrtf(s1 * (1.0f / HD) + EPS);
;         u32x4 w0, w1;
;         w0.x = pk2(v[0] * r0 * g0[0], v[1] * r0 * g0[1]); w0.y = pk2(v[2] * r0 * g0[2], v[3] * r0 * g0[3]); w0.z = pk2(v[4] * r0 * g1[0], v[5] * r0 * g1[1]); w0.w = pk2(v[6] * r0 * g1[2], v[7] * r0 * g1[3]);
;         w1.x = pk2(u[0] * r1 * g0[0], u[1] * r1 * g0[1]); w1.y = pk2(u[2] * r1 * g0[2], u[3] * r1 * g0[3]); w1.z = pk2(u[4] * r1 * g1[0], u[5] * r1 * g1[1]); w1.w = pk2(u[6] * r1 * g1[2], u[7] * r1 * g1[3]);
;         *(u32x4*)rowp0 = w0; *(u32x4*)rowp1 = w1;
.LBB0_246:
	v_ashrrev_i32_e32 v0, 31, v3
	s_movk_i32 s2, 0x4000
	v_lshrrev_b32_e32 v0, 21, v0
	v_cmp_gt_i32_e32 vcc, s2, v3
	v_add_u32_e32 v0, v3, v0
	v_ashrrev_i32_e32 v0, 11, v0
	v_cndmask_b32_e64 v7, 20, 8, vcc
	v_add_u32_e32 v8, v7, v0
	v_cmp_gt_u32_e32 vcc, 30, v8
	v_mul_i32_i24_e32 v15, 0x800, v0
	v_lshlrev_b32_e32 v7, 3, v15
	v_cndmask_b32_e64 v0, v234, 64, vcc
	v_cmp_lt_i32_e32 vcc, 15, v8
	v_ashrrev_i32_e32 v9, 31, v8
	v_sub_u32_e32 v16, v14, v7
	v_cndmask_b32_e32 v0, 40, v0, vcc
	v_lshl_add_u64 v[18:19], s[14:15], 0, v[0:1]
	global_load_dwordx2 v[24:25], v[18:19], off
	v_lshlrev_b64 v[8:9], 14, v[8:9]
	v_ashrrev_i32_e32 v17, 31, v16
	v_lshl_add_u64 v[8:9], v[8:9], 0, v[16:17]
	v_or_b32_e32 v8, v8, v2
	v_lshlrev_b64 v[8:9], 8, v[8:9]
	v_lshl_add_u64 v[8:9], v[4:5], 0, v[8:9]
	v_mov_b32_e32 v7, v1
	v_add_u32_e32 v3, s9, v3
	s_movk_i32 s2, 0x5fff
	v_cmp_lt_i32_e32 vcc, s2, v3
	s_brev_b32 s2, 60
	s_or_b64 s[10:11], vcc, s[10:11]
	v_add_u32_e32 v14, s12, v14
	s_waitcnt vmcnt(0)
	v_mov_b32_e32 v16, v160
	v_mov_b32_e32 v17, v161
	v_mov_b32_e32 v18, v162
	v_mov_b32_e32 v19, v163
	v_mov_b32_e32 v20, v164
	v_mov_b32_e32 v21, v165
	v_mov_b32_e32 v22, v166
	v_mov_b32_e32 v23, v167
	v_lshl_add_u64 v[24:25], s[16:17], 2, v[24:25]
	v_lshl_add_u64 v[28:29], v[24:25], 0, v[6:7]
	global_load_dwordx4 v[24:27], v[28:29], off offset:16
	s_nop 0
	global_load_dwordx4 v[28:31], v[28:29], off
	v_ashrrev_i32_e32 v176, 31, v3
	v_lshrrev_b32_e32 v176, 21, v176
	v_cmp_gt_i32_e32 vcc, 0x4000, v3
	v_add_u32_e32 v176, v3, v176
	v_ashrrev_i32_e32 v176, 11, v176
	v_cndmask_b32_e64 v177, 20, 8, vcc
	v_add_u32_e32 v178, v177, v176
	v_mul_i32_i24_e32 v180, 0x800, v176
	v_lshlrev_b32_e32 v177, 3, v180
	v_ashrrev_i32_e32 v179, 31, v178
	v_sub_u32_e32 v182, v14, v177
	v_lshlrev_b64 v[178:179], 14, v[178:179]
	v_ashrrev_i32_e32 v183, 31, v182
	v_lshl_add_u64 v[178:179], v[178:179], 0, v[182:183]
	v_or_b32_e32 v178, v178, v2
	v_lshlrev_b64 v[178:179], 8, v[178:179]
	v_lshl_add_u64 v[178:179], v[4:5], 0, v[178:179]
	v_cmp_lt_i32_e32 vcc, 0x5fff, v3
	s_nop 1
	v_cndmask_b32_e32 v178, v178, v8, vcc
	v_cndmask_b32_e32 v179, v179, v9, vcc
	global_load_dwordx4 v[160:163], v[178:179], off
	global_load_dwordx4 v[164:167], v[178:179], off offset:1024
	v_and_b32_e32 v37, 0xffff0000, v16
	v_and_b32_e32 v41, 0xffff0000, v20
	v_lshlrev_b32_e32 v32, 16, v19
	v_and_b32_e32 v33, 0xffff0000, v19
	v_lshlrev_b32_e32 v34, 16, v18
	v_and_b32_e32 v35, 0xffff0000, v18
	v_lshlrev_b32_e32 v18, 16, v17
	v_and_b32_e32 v19, 0xffff0000, v17
	v_lshlrev_b32_e32 v36, 16, v16
	v_lshlrev_b32_e32 v16, 16, v23
	v_and_b32_e32 v17, 0xffff0000, v23
	v_lshlrev_b32_e32 v38, 16, v22
	v_and_b32_e32 v39, 0xffff0000, v22
	v_lshlrev_b32_e32 v22, 16, v21
	v_and_b32_e32 v23, 0xffff0000, v21
	v_lshlrev_b32_e32 v40, 16, v20
	v_mov_b32_e32 v54, v41
	v_mov_b32_e32 v55, v37
	v_pk_mul_f32 v[20:21], v[32:33], v[32:33]
	v_pk_mul_f32 v[42:43], v[34:35], v[34:35]
	v_pk_mul_f32 v[44:45], v[18:19], v[18:19]
	v_pk_mul_f32 v[46:47], v[16:17], v[16:17]
	v_pk_mul_f32 v[48:49], v[38:39], v[38:39]
	v_pk_mul_f32 v[50:51], v[22:23], v[22:23]
	v_mov_b32_e32 v52, v40
	v_mov_b32_e32 v53, v36
	v_pk_mul_f32 v[54:55], v[54:55], v[54:55]
	v_mov_b32_e32 v56, v50
	v_mov_b32_e32 v57, v44
	v_mov_b32_e32 v44, v51
	v_mov_b32_e32 v50, v48
	v_mov_b32_e32 v51, v42
	v_mov_b32_e32 v42, v49
	v_mov_b32_e32 v48, v46
	v_mov_b32_e32 v49, v20
	v_mov_b32_e32 v20, v47
	v_pk_fma_f32 v[46:47], v[52:53], v[52:53], v[54:55]
	s_nop 0
	v_pk_add_f32 v[46:47], v[56:57], v[46:47]
	s_nop 0
	v_pk_add_f32 v[44:45], v[44:45], v[46:47]
	s_nop 0
	v_pk_add_f32 v[44:45], v[50:51], v[44:45]
	s_nop 0
	v_pk_add_f32 v[42:43], v[42:43], v[44:45]
	s_nop 0
	v_pk_add_f32 v[42:43], v[48:49], v[42:43]
	s_nop 0
	v_pk_add_f32 v[20:21], v[20:21], v[42:43]
	ds_bpermute_b32 v43, v10, v21
	ds_bpermute_b32 v42, v10, v20
	s_waitcnt lgkmcnt(0)
	v_pk_add_f32 v[20:21], v[20:21], v[42:43]
	ds_bpermute_b32 v43, v11, v21
	ds_bpermute_b32 v42, v11, v20
	s_waitcnt lgkmcnt(0)
	v_pk_add_f32 v[20:21], v[20:21], v[42:43]
	ds_bpermute_b32 v43, v12, v21
	ds_bpermute_b32 v42, v12, v20
	s_waitcnt lgkmcnt(0)
	v_pk_add_f32 v[20:21], v[20:21], v[42:43]
	ds_bpermute_b32 v43, v13, v21
	ds_bpermute_b32 v42, v13, v20
	s_waitcnt lgkmcnt(0)
	v_pk_add_f32 v[20:21], v[20:21], v[42:43]
	s_nop 0
	v_pk_fma_f32 v[20:21], v[20:21], s[2:3], v[188:189] op_sel_hi:[1,0,0]
	s_nop 0
	v_mul_f32_e32 v0, 0x4b800000, v21
	v_cmp_gt_f32_e64 s[2:3], s52, v21
	v_mul_f32_e32 v7, 0x4b800000, v20
	v_cmp_gt_f32_e32 vcc, s52, v20
	v_cndmask_b32_e64 v0, v21, v0, s[2:3]
	v_rsq_f32_e32 v0, v0
	v_cndmask_b32_e32 v7, v20, v7, vcc
	v_rsq_f32_e32 v7, v7
	v_mul_f32_e32 v15, 0x45800000, v0
	v_cndmask_b32_e64 v0, v0, v15, s[2:3]
	v_mul_f32_e32 v20, 0x45800000, v7
	v_cndmask_b32_e32 v20, v7, v20, vcc
	v_pk_mul_f32 v[36:37], v[0:1], v[36:37] op_sel_hi:[0,1]
	v_pk_mul_f32 v[18:19], v[0:1], v[18:19] op_sel_hi:[0,1]
	v_pk_mul_f32 v[34:35], v[0:1], v[34:35] op_sel_hi:[0,1]
	v_pk_mul_f32 v[32:33], v[0:1], v[32:33] op_sel_hi:[0,1]
	v_pk_mul_f32 v[40:41], v[20:21], v[40:41] op_sel_hi:[0,1]
	v_pk_mul_f32 v[22:23], v[20:21], v[22:23] op_sel_hi:[0,1]
	v_pk_mul_f32 v[38:39], v[20:21], v[38:39] op_sel_hi:[0,1]
	v_pk_mul_f32 v[16:17], v[20:21], v[16:17] op_sel_hi:[0,1]
	s_waitcnt vmcnt(2)
	v_pk_mul_f32 v[20:21], v[28:29], v[36:37]
	v_pk_mul_f32 v[18:19], v[30:31], v[18:19]
	v_pk_mul_f32 v[34:35], v[24:25], v[34:35]
	v_pk_mul_f32 v[32:33], v[26:27], v[32:33]
	v_pk_mul_f32 v[28:29], v[28:29], v[40:41]
	v_pk_mul_f32 v[22:23], v[30:31], v[22:23]
	v_pk_mul_f32 v[24:25], v[24:25], v[38:39]
	v_pk_mul_f32 v[26:27], v[26:27], v[16:17]
	v_cvt_pk_bf16_f32 v16, v20, v21
	v_cvt_pk_bf16_f32 v17, v18, v19
	v_cvt_pk_bf16_f32 v18, v34, v35
	v_cvt_pk_bf16_f32 v19, v32, v33
	v_cvt_pk_bf16_f32 v20, v28, v29
	v_cvt_pk_bf16_f32 v21, v22, v23
	v_cvt_pk_bf16_f32 v22, v24, v25
	v_cvt_pk_bf16_f32 v23, v26, v27
	global_store_dwordx4 v[8:9], v[16:19], off
	global_store_dwordx4 v[8:9], v[20:23], off offset:1024
	s_andn2_b64 exec, exec, s[10:11]
	s_cbranch_execnz .LBB0_246
